# phase C bias-table load as straight-line code (five loads in flight, one wait)
# speedup vs baseline: 1.0017x; 1.0017x over previous
.LBB0_251:
	s_mov_b64 s[2:3], s[36:37]
	s_waitcnt vmcnt(17)
	v_mov_b32_e32 v0, v224
	s_movk_i32 s0, 0xa00
	s_nop 0
	v_cmp_gt_i32_e32 vcc, s0, v0
	s_and_saveexec_b64 s[0:1], vcc
	s_cbranch_execz .LBB0_259
	s_load_dwordx2 s[2:3], s[2:3], 0x60
	v_readlane_b32 s4, v254, 21
	s_lshl_b32 s8, s4, 3
	s_add_i32 s9, s24, 0x12000
	s_movk_i32 s5, 0x804
	s_mov_b32 s6, 0x66666667
	v_lshl_add_u32 v9, v0, 2, s9
	v_mul_hi_i32 v2, v0, s6
	v_ashrrev_i32_e32 v2, 7, v2
	v_mul_u32_u24_e32 v3, 0x140, v2
	v_sub_u32_e32 v3, v0, v3
	v_add_u32_e32 v2, s8, v2
	v_lshlrev_b32_e32 v3, 2, v3
	v_mad_u32_u24 v3, v2, s5, v3
	s_waitcnt lgkmcnt(0)
	global_load_dword v10, v3, s[2:3] offset:772
	v_add_u32_e32 v1, 0x200, v0
	v_mul_hi_i32 v2, v1, s6
	v_ashrrev_i32_e32 v2, 7, v2
	v_mul_u32_u24_e32 v3, 0x140, v2
	v_sub_u32_e32 v3, v1, v3
	v_add_u32_e32 v2, s8, v2
	v_lshlrev_b32_e32 v3, 2, v3
	v_mad_u32_u24 v3, v2, s5, v3
	global_load_dword v11, v3, s[2:3] offset:772
	v_add_u32_e32 v1, 0x400, v0
	v_mul_hi_i32 v2, v1, s6
	v_ashrrev_i32_e32 v2, 7, v2
	v_mul_u32_u24_e32 v3, 0x140, v2
	v_sub_u32_e32 v3, v1, v3
	v_add_u32_e32 v2, s8, v2
	v_lshlrev_b32_e32 v3, 2, v3
	v_mad_u32_u24 v3, v2, s5, v3
	global_load_dword v12, v3, s[2:3] offset:772
	v_add_u32_e32 v1, 0x600, v0
	v_mul_hi_i32 v2, v1, s6
	v_ashrrev_i32_e32 v2, 7, v2
	v_mul_u32_u24_e32 v3, 0x140, v2
	v_sub_u32_e32 v3, v1, v3
	v_add_u32_e32 v2, s8, v2
	v_lshlrev_b32_e32 v3, 2, v3
	v_mad_u32_u24 v3, v2, s5, v3
	global_load_dword v13, v3, s[2:3] offset:772
	v_add_u32_e32 v1, 0x800, v0
	v_mul_hi_i32 v2, v1, s6
	v_ashrrev_i32_e32 v2, 7, v2
	v_mul_u32_u24_e32 v3, 0x140, v2
	v_sub_u32_e32 v3, v1, v3
	v_add_u32_e32 v2, s8, v2
	v_lshlrev_b32_e32 v3, 2, v3
	v_mad_u32_u24 v3, v2, s5, v3
	global_load_dword v14, v3, s[2:3] offset:772
	s_waitcnt vmcnt(0)
	v_mul_f32_e32 v10, 0x3fb8aa3b, v10
	v_mul_f32_e32 v11, 0x3fb8aa3b, v11
	v_mul_f32_e32 v12, 0x3fb8aa3b, v12
	v_mul_f32_e32 v13, 0x3fb8aa3b, v13
	v_mul_f32_e32 v14, 0x3fb8aa3b, v14
	ds_write_b32 v9, v10
	ds_write_b32 v9, v11 offset:2048
	ds_write_b32 v9, v12 offset:4096
	ds_write_b32 v9, v13 offset:6144
	ds_write_b32 v9, v14 offset:8192
